# phase-0 conversion offload enlarged per slot-capacity timing: ranges 12288/16384/19456 (6 item rounds left in phase 0; 4/3/3 rounds per idle wave in phases 1/5/7)
# speedup vs baseline: 1.0056x; 1.0056x over previous
.LBB0_20:
	s_lshr_b32 s89, s77, 6
	s_load_dwordx16 s[8:23], s[0:1], 0x40
	s_cmp_lt_i32 s28, 1
	s_cselect_b64 s[0:1], -1, 0
	s_cmp_gt_i32 s29, 0
	s_cselect_b64 s[2:3], -1, 0
	s_and_b64 s[2:3], s[0:1], s[2:3]
	s_andn2_b64 vcc, exec, s[2:3]
	v_and_b32_e32 v227, 63, v226
	s_cbranch_vccnz .LBB0_42
	s_mov_b32 s96, 0
	s_mov_b32 s97, 0x3000
	s_lshl_b32 s0, s76, 3
	s_add_i32 s4, s0, s89

.Lp0call_1:
	v_writelane_b32 v251, s0, 0
	v_writelane_b32 v251, s1, 1
	v_writelane_b32 v251, s4, 2
	v_writelane_b32 v251, s5, 3
	v_writelane_b32 v251, s26, 4
	v_writelane_b32 v251, s27, 5
	v_writelane_b32 v251, s30, 6
	v_writelane_b32 v251, s31, 7
	v_writelane_b32 v251, s34, 8
	v_writelane_b32 v251, s35, 9
	v_writelane_b32 v251, s52, 10
	v_writelane_b32 v251, s53, 11
	v_writelane_b32 v251, s54, 12
	v_writelane_b32 v251, s55, 13
	v_writelane_b32 v251, s56, 14
	v_writelane_b32 v251, s57, 15
	v_writelane_b32 v251, s58, 16
	v_writelane_b32 v251, s59, 17
	v_writelane_b32 v251, s60, 18
	v_writelane_b32 v251, s61, 19
	v_writelane_b32 v251, s62, 20
	v_writelane_b32 v251, s63, 21
	v_writelane_b32 v251, s64, 22
	v_writelane_b32 v251, s65, 23
	v_writelane_b32 v251, s66, 24
	v_writelane_b32 v251, s67, 25
	v_writelane_b32 v251, s68, 26
	v_writelane_b32 v251, s69, 27
	v_writelane_b32 v251, s70, 28
	v_writelane_b32 v251, s71, 29
	v_writelane_b32 v251, s33, 30
	v_writelane_b32 v251, s40, 31
	v_writelane_b32 v251, s41, 32
	v_writelane_b32 v251, s42, 33
	v_writelane_b32 v251, s43, 34
	v_writelane_b32 v251, s89, 35
	v_writelane_b32 v251, vcc_lo, 36
	v_writelane_b32 v251, vcc_hi, 37
	s_nop 1
	v_readlane_b32 s0, v250, 0
	v_readlane_b32 s1, v250, 1
	s_nop 3
	s_sub_u32 s0, s0, 0x90
	s_subb_u32 s1, s1, 0
	s_load_dwordx4 s[40:43], s[0:1], 0x10
	s_lshr_b32 s89, s77, 6
	s_sub_i32 s4, s6, 0x80
	s_lshl_b32 s4, s4, 3
	s_add_i32 s4, s4, s89
	s_add_i32 s4, s4, 0x3000
	s_mov_b32 s33, 0x80
	s_mov_b32 s97, 0x4000
	s_mov_b32 s96, 1
	s_waitcnt vmcnt(0) lgkmcnt(0)
	s_branch .Lp0_entry

.Lp0call_2:
	v_writelane_b32 v251, s0, 0
	v_writelane_b32 v251, s1, 1
	v_writelane_b32 v251, s4, 2
	v_writelane_b32 v251, s5, 3
	v_writelane_b32 v251, s26, 4
	v_writelane_b32 v251, s27, 5
	v_writelane_b32 v251, s30, 6
	v_writelane_b32 v251, s31, 7
	v_writelane_b32 v251, s34, 8
	v_writelane_b32 v251, s35, 9
	v_writelane_b32 v251, s52, 10
	v_writelane_b32 v251, s53, 11
	v_writelane_b32 v251, s54, 12
	v_writelane_b32 v251, s55, 13
	v_writelane_b32 v251, s56, 14
	v_writelane_b32 v251, s57, 15
	v_writelane_b32 v251, s58, 16
	v_writelane_b32 v251, s59, 17
	v_writelane_b32 v251, s60, 18
	v_writelane_b32 v251, s61, 19
	v_writelane_b32 v251, s62, 20
	v_writelane_b32 v251, s63, 21
	v_writelane_b32 v251, s64, 22
	v_writelane_b32 v251, s65, 23
	v_writelane_b32 v251, s66, 24
	v_writelane_b32 v251, s67, 25
	v_writelane_b32 v251, s68, 26
	v_writelane_b32 v251, s69, 27
	v_writelane_b32 v251, s70, 28
	v_writelane_b32 v251, s71, 29
	v_writelane_b32 v251, s33, 30
	v_writelane_b32 v251, s40, 31
	v_writelane_b32 v251, s41, 32
	v_writelane_b32 v251, s42, 33
	v_writelane_b32 v251, s43, 34
	v_writelane_b32 v251, s89, 35
	v_writelane_b32 v251, vcc_lo, 36
	v_writelane_b32 v251, vcc_hi, 37
	s_nop 1
	v_readlane_b32 s0, v250, 0
	v_readlane_b32 s1, v250, 1
	s_nop 3
	s_sub_u32 s0, s0, 0x90
	s_subb_u32 s1, s1, 0
	s_load_dwordx4 s[40:43], s[0:1], 0x10
	s_lshr_b32 s89, s77, 6
	s_sub_i32 s4, s6, 0x80
	s_lshl_b32 s4, s4, 3
	s_add_i32 s4, s4, s89
	s_add_i32 s4, s4, 0x4000
	s_mov_b32 s33, 0x80
	s_mov_b32 s97, 0x4c00
	s_mov_b32 s96, 2
	s_waitcnt vmcnt(0) lgkmcnt(0)
	s_branch .Lp0_entry

.Lp0call_3:
	v_writelane_b32 v251, s0, 0
	v_writelane_b32 v251, s1, 1
	v_writelane_b32 v251, s4, 2
	v_writelane_b32 v251, s5, 3
	v_writelane_b32 v251, s26, 4
	v_writelane_b32 v251, s27, 5
	v_writelane_b32 v251, s30, 6
	v_writelane_b32 v251, s31, 7
	v_writelane_b32 v251, s34, 8
	v_writelane_b32 v251, s35, 9
	v_writelane_b32 v251, s52, 10
	v_writelane_b32 v251, s53, 11
	v_writelane_b32 v251, s54, 12
	v_writelane_b32 v251, s55, 13
	v_writelane_b32 v251, s56, 14
	v_writelane_b32 v251, s57, 15
	v_writelane_b32 v251, s58, 16
	v_writelane_b32 v251, s59, 17
	v_writelane_b32 v251, s60, 18
	v_writelane_b32 v251, s61, 19
	v_writelane_b32 v251, s62, 20
	v_writelane_b32 v251, s63, 21
	v_writelane_b32 v251, s64, 22
	v_writelane_b32 v251, s65, 23
	v_writelane_b32 v251, s66, 24
	v_writelane_b32 v251, s67, 25
	v_writelane_b32 v251, s68, 26
	v_writelane_b32 v251, s69, 27
	v_writelane_b32 v251, s70, 28
	v_writelane_b32 v251, s71, 29
	v_writelane_b32 v251, s33, 30
	v_writelane_b32 v251, s40, 31
	v_writelane_b32 v251, s41, 32
	v_writelane_b32 v251, s42, 33
	v_writelane_b32 v251, s43, 34
	v_writelane_b32 v251, s89, 35
	v_writelane_b32 v251, vcc_lo, 36
	v_writelane_b32 v251, vcc_hi, 37
	s_nop 1
	v_readlane_b32 s0, v250, 0
	v_readlane_b32 s1, v250, 1
	s_nop 3
	s_sub_u32 s0, s0, 0x90
	s_subb_u32 s1, s1, 0
	s_load_dwordx4 s[40:43], s[0:1], 0x10
	s_lshr_b32 s89, s77, 6
	s_sub_i32 s4, s6, 0x80
	s_lshl_b32 s4, s4, 3
	s_add_i32 s4, s4, s89
	s_add_i32 s4, s4, 0x4c00
	s_mov_b32 s33, 0x80
	s_mov_b32 s97, 0x5800
	s_mov_b32 s96, 3
	s_waitcnt vmcnt(0) lgkmcnt(0)
	s_branch .Lp0_entry
